# P2: non-skinny workgroups pre-touch the W1O rows of their XCD's two skinny workgroups (L2 warm-up)
# speedup vs baseline: 1.0036x; 1.0002x over previous
; __global__ void __launch_bounds__(NT, 2) hymba_fwd(Args args) {
;     ...
;         if (bid < 16) {
;             const int fr = lane & 15, fq = lane >> 4;
;             f32x4 acc[4];
; #pragma unroll
;             for (int t = 0; t < 4; ++t) acc[t] = (f32x4){0.f, 0.f, 0.f, 0.f};
;             const bf16* ap = ACT + (size_t)(MROW0 + fr) * DFF + wave * 352 + fq * 8;
;             const bf16* bp = W1O + (size_t)(64 * bid + fr) * DFF + wave * 352 + fq * 8;
;     ...
;         pg8::Gemm g{ACT, W1O, NTOK, D, DFF}; pg8::StaticOrder S; S.init(NTOK, D, G, bid);
.LBB0_375:
	s_load_dwordx2 s[8:9], s[0:1], 0x80
	s_cmp_lt_i32 s76, 3
	s_cselect_b64 s[6:7], -1, 0
	s_waitcnt lgkmcnt(0)
	s_add_u32 s10, s8, 0x300000
	s_addc_u32 s11, s9, 0
	s_and_b64 s[16:17], s[6:7], s[4:5]
	s_andn2_b64 vcc, exec, s[16:17]
	s_cbranch_vccnz .LBB0_428
	s_cmp_lt_i32 s68, 16
	s_cbranch_scc1 .LBB0_378
	s_waitcnt vmcnt(29)
	v_lshrrev_b32_e32 v2, 5, v179
	v_and_b32_e32 v108, 15, v179
	s_lshr_b32 s99, s68, 3
	s_sub_u32 s99, s99, 2
	s_cmp_gt_u32 s99, 29
	s_cbranch_scc1 .Lw1o_pf_skip
	s_and_b32 s98, s68, 7
	s_cmp_ge_u32 s99, 15
	s_cselect_b32 s100, 8, 0
	s_cselect_b32 s101, 15, 0
	s_add_u32 s98, s98, s100
	s_sub_u32 s99, s99, s101
	s_mul_i32 s98, s98, 0x58000
	s_mul_i32 s99, s99, 0x6000
	s_add_u32 s98, s98, s99
	v_lshrrev_b32_e32 v226, 6, v179
	v_mul_u32_u24_e32 v226, 0xc00, v226
	v_and_b32_e32 v227, 63, v179
	v_lshl_add_u32 v226, v227, 4, v226
	v_add_u32_e32 v226, s98, v226
	global_load_dwordx4 v[228:231], v226, s[12:13]
	global_load_dwordx4 v[228:231], v226, s[12:13] offset:1024
	global_load_dwordx4 v[228:231], v226, s[12:13] offset:2048
.Lw1o_pf_skip:
	s_cbranch_execz .LBB0_379
	s_branch .LBB0_382
